# v18 + static priority raise for the half-workgroup that starts first (wr == 0) in the GEMM phases, per-cluster flips deleted
# speedup vs baseline: 1.0056x; 1.0056x over previous
; #define PG8_STAGE(bufoff, gbase, voff) do { _Pragma("unroll") for (int _i = 0; _i < 2; ++_i) \
;         __builtin_amdgcn_global_load_lds((const unsigned*)((const char*)(gbase) + (voff)[_i]), (LAS unsigned*)(lds + (bufoff) + ldsw + _i * 8192), 16, 0, 0); } while (0)
; #define PG8_BAR __builtin_amdgcn_s_barrier()
; template <class Epi, bool ALIGN_EPI = false, bool SP2 = true>
; __device__ __forceinline__ void gemm_phase(LAS unsigned char* lds, const Gemm g, const StaticOrder& S, const Epi& E) {
;     const int tid = threadIdx.x, wid = __builtin_amdgcn_readfirstlane(tid >> 6), lane = tid & 63, wr = wid >> 2, wc = wid & 3, fr = lane & 15, fq = lane >> 4;
;     const int K = g.K, nt = K / BK;
;     unsigned voffA[2], voffB[2];
; #pragma unroll
;     for (int i = 0; i < 2; ++i) { int R, C; stage_rc(tid * 16 + i * 8192, R, C); const int Rb = (R & ~31) + perm32(R & 31);
;         voffA[i] = (unsigned)(R * K + C) * 2u; voffB[i] = (unsigned)(Rb * K + C) * 2u; }
;     const size_t kstep = (size_t)(BK * 2);
;     const size_t hstep = (size_t)HALF * K * 2;
;     const size_t tstep = 2 * hstep;
;     const unsigned ldsw = (unsigned)wid * 1024u;
;     const int aoff = lds_byte(wr * 64 + fr, fq * 8), boff = lds_byte(wc * 32 + fr, fq * 8);
;     ...
;     Unit cur, nxt; int ui = 0;
;     if (!S.next(0, cur)) return;
;     f32x4 acc[2][2][4][2];
; #pragma unroll
;     for (int a = 0; a < 2; ++a)
; #pragma unroll
;         for (int b = 0; b < 2; ++b)
; #pragma unroll
;             for (int m = 0; m < 4; ++m)
; #pragma unroll
;                 for (int n = 0; n < 2; ++n) acc[a][b][m][n] = (f32x4){0.f, 0.f, 0.f, 0.f};
;     bf16x8 At[4][2], B0[2][2], B1[2][2];
;     const char* cA = (const char*)g.A + (size_t)cur.pm * tstep; const char* cB = (const char*)g.Bt + (size_t)(cur.pn + (cur.pm >= g.bsplit ? g.badd : 0)) * tstep;
;     if constexpr (SP2) {
;         PG8_STAGE(PG8_SB(0, 0), cB, voffB); PG8_STAGE(PG8_SB(0, 1), cB + hstep, voffB); PG8_STAGE(PG8_SA(0, 0), cA, voffA); PG8_STAGE(PG8_SA(0, 1), cA + hstep, voffA);
;         if (wr == 1) PG8_BAR;
.LBB0_146:
	s_andn2_b64 vcc, exec, s[4:5]
	s_cbranch_vccnz .LBB0_182
	s_waitcnt vmcnt(5)
	v_lshrrev_b32_e32 v2, 1, v164
	v_lshrrev_b32_e32 v3, 5, v164
	v_and_b32_e32 v2, 24, v2
	v_and_b32_e32 v3, 4, v3
	s_waitcnt vmcnt(4)
	v_bfe_u32 v4, v164, 2, 2
	v_lshlrev_b32_e32 v0, 4, v164
	v_and_b32_e32 v1, 32, v164
	s_waitcnt vmcnt(3)
	v_bfe_u32 v10, v164, 2, 4
	v_or3_b32 v2, v3, v4, v2
	v_lshrrev_b32_e32 v3, 3, v164
	s_movk_i32 s3, 0x70
	v_bitop3_b32 v8, v0, v1, 48 bitop3:0x6c
	v_and_b32_e32 v9, 64, v164
	v_and_or_b32 v4, v3, s3, v10
	s_movk_i32 s3, 0x60
	v_add_u32_e32 v11, 0x2000, v0
	v_or_b32_e32 v1, v8, v9
	v_and_or_b32 v3, v3, s3, v2
	v_lshrrev_b32_e32 v0, 7, v11
	s_movk_i32 s3, 0xf0
	s_lshr_b32 s5, s6, 6
	v_lshl_or_b32 v130, v3, 12, v1
	v_and_or_b32 v3, v0, s3, v10
	s_movk_i32 s3, 0xe0
	s_ashr_i32 s19, s18, 31
	s_ashr_i32 s71, s70, 31
	v_and_or_b32 v0, v0, s3, v2
	s_lshr_b32 s4, s6, 8
	s_lshl_b32 s3, s5, 10
	s_lshl_b64 s[26:27], s[18:19], 20
	s_lshl_b64 s[36:37], s[70:71], 20
	s_add_u32 s74, s14, s36
	s_addc_u32 s75, s15, s37
	s_add_i32 s71, s3, 0
	s_add_i32 m0, s71, 0x10000
	v_lshl_or_b32 v134, v0, 12, v1
	global_load_lds_dwordx4 v130, s[74:75]
	s_add_i32 m0, s71, 0x12000
	s_add_u32 s36, s74, 0x80000
	global_load_lds_dwordx4 v134, s[74:75]
	s_addc_u32 s37, s75, 0
	s_add_i32 m0, s71, 0x14000
	v_lshl_or_b32 v128, v4, 12, v1
	global_load_lds_dwordx4 v130, s[36:37]
	s_add_i32 m0, s71, 0x16000
	s_add_u32 s72, s20, s26
	s_addc_u32 s73, s21, s27
	s_add_i32 s78, s71, 0x2000
	global_load_lds_dwordx4 v134, s[36:37]
	s_mov_b32 m0, s71
	s_add_u32 s26, s72, 0x80000
	v_lshl_or_b32 v132, v3, 12, v1
	global_load_lds_dwordx4 v128, s[72:73]
	s_mov_b32 m0, s78
	s_addc_u32 s27, s73, 0
	s_add_i32 s79, s71, 0x4000
	global_load_lds_dwordx4 v132, s[72:73]
	s_mov_b32 m0, s79
	s_add_i32 s80, s71, 0x6000
	global_load_lds_dwordx4 v128, s[26:27]
	s_mov_b32 m0, s80
	v_mov_b32_e32 v137, 0
	global_load_lds_dwordx4 v132, s[26:27]
	v_mov_b32_e32 v131, v137
	v_mov_b32_e32 v135, v137
	v_mov_b32_e32 v129, v137
	v_mov_b32_e32 v133, v137
	s_cmp_eq_u32 s4, 1
	s_mov_b32 s19, 0
	v_lshl_add_u64 v[6:7], s[74:75], 0, v[130:131]
	v_lshl_add_u64 v[4:5], s[74:75], 0, v[134:135]
	v_lshl_add_u64 v[0:1], s[72:73], 0, v[128:129]
	s_cselect_b64 s[26:27], -1, 0
	s_cmp_lg_u32 s4, 1
	v_lshl_add_u64 v[2:3], s[72:73], 0, v[132:133]
	s_setprio 1
	s_cbranch_scc1 .LBB0_149
	s_barrier
	s_setprio 0

; #define PG8_STAGE(bufoff, gbase, voff) do { _Pragma("unroll") for (int _i = 0; _i < 2; ++_i) \
;         __builtin_amdgcn_global_load_lds((const unsigned*)((const char*)(gbase) + (voff)[_i]), (LAS unsigned*)(lds + (bufoff) + ldsw + _i * 8192), 16, 0, 0); } while (0)
; #define PG8_BAR __builtin_amdgcn_s_barrier()
; template <class Epi, bool ALIGN_EPI = false, bool SP2 = true>
; __device__ __forceinline__ void gemm_phase(LAS unsigned char* lds, const Gemm g, const StaticOrder& S, const Epi& E) {
;     const int tid = threadIdx.x, wid = __builtin_amdgcn_readfirstlane(tid >> 6), lane = tid & 63, wr = wid >> 2, wc = wid & 3, fr = lane & 15, fq = lane >> 4;
;     const int K = g.K, nt = K / BK;
;     unsigned voffA[2], voffB[2];
; #pragma unroll
;     for (int i = 0; i < 2; ++i) { int R, C; stage_rc(tid * 16 + i * 8192, R, C); const int Rb = (R & ~31) + perm32(R & 31);
;         voffA[i] = (unsigned)(R * K + C) * 2u; voffB[i] = (unsigned)(Rb * K + C) * 2u; }
;     const size_t kstep = (size_t)(BK * 2);
;     const size_t hstep = (size_t)HALF * K * 2;
;     const size_t tstep = 2 * hstep;
;     const unsigned ldsw = (unsigned)wid * 1024u;
;     const int aoff = lds_byte(wr * 64 + fr, fq * 8), boff = lds_byte(wc * 32 + fr, fq * 8);
;     ...
;     Unit cur, nxt; int ui = 0;
;     if (!S.next(0, cur)) return;
;     f32x4 acc[2][2][4][2];
; #pragma unroll
;     for (int a = 0; a < 2; ++a)
; #pragma unroll
;         for (int b = 0; b < 2; ++b)
; #pragma unroll
;             for (int m = 0; m < 4; ++m)
; #pragma unroll
;                 for (int n = 0; n < 2; ++n) acc[a][b][m][n] = (f32x4){0.f, 0.f, 0.f, 0.f};
;     bf16x8 At[4][2], B0[2][2], B1[2][2];
;     const char* cA = (const char*)g.A + (size_t)cur.pm * tstep; const char* cB = (const char*)g.Bt + (size_t)(cur.pn + (cur.pm >= g.bsplit ? g.badd : 0)) * tstep;
;     if constexpr (SP2) {
;         PG8_STAGE(PG8_SB(0, 0), cB, voffB); PG8_STAGE(PG8_SB(0, 1), cB + hstep, voffB); PG8_STAGE(PG8_SA(0, 0), cA, voffA); PG8_STAGE(PG8_SA(0, 1), cA + hstep, voffA);
;         if (wr == 1) PG8_BAR;
.LBB0_297:
	s_lshr_b32 s0, s68, 6
	s_ashr_i32 s1, s4, 3
	s_lshr_b32 s4, s68, 8
	s_lshl_b32 s69, s0, 10
	s_add_u32 s70, s40, 0x3200000
	s_addc_u32 s71, s41, 0
	s_add_i32 s1, s5, s1
	s_ashr_i32 s5, s1, 31
	s_lshr_b32 s5, s5, 27
	s_add_i32 s5, s1, s5
	s_ashr_i32 s6, s5, 5
	s_andn2_b32 s5, s5, 31
	s_sub_i32 s1, s1, s5
	s_bfe_i32 s5, s1, 0x80000
	s_bfe_u32 s5, s5, 0x2000d
	s_add_i32 s5, s1, s5
	s_bfe_i32 s7, s5, 0x80000
	s_and_b32 s5, s5, 0xfc
	s_sub_i32 s1, s1, s5
	s_lshl_b32 s6, s6, 2
	s_sext_i32_i8 s1, s1
	s_add_i32 s36, s6, s1
	s_and_b32 s36, s2, 7
	s_lshl_b32 s36, s36, 2
	s_bfe_u32 s1, s2, 0x20003
	s_or_b32 s36, s36, s1
	s_sext_i32_i16 s7, s7
	s_ashr_i32 s37, s36, 31
	s_ashr_i32 s84, s7, 2
	s_lshr_b32 s84, s2, 5
	s_lshl_b64 s[6:7], s[36:37], 17
	s_cmp_gt_i32 s36, 31
	s_cselect_b32 s1, 8, 0
	s_add_i32 s18, s1, s84
	s_ashr_i32 s19, s18, 31
	s_lshl_b64 s[18:19], s[18:19], 17
	s_add_u32 s62, s58, s18
	s_addc_u32 s63, s59, s19
	s_add_i32 s37, s69, 0
	v_lshl_or_b32 v42, v64, 9, v62
	s_add_i32 m0, s37, 0x10000
	v_lshl_or_b32 v46, v66, 9, v62
	global_load_lds_dwordx4 v42, s[62:63]
	s_add_i32 m0, s37, 0x12000
	s_add_u32 s18, s62, 0x10000
	global_load_lds_dwordx4 v46, s[62:63]
	s_addc_u32 s19, s63, 0
	s_add_i32 m0, s37, 0x14000
	v_lshl_or_b32 v40, v63, 9, v62
	global_load_lds_dwordx4 v42, s[18:19]
	s_add_i32 m0, s37, 0x16000
	s_add_u32 s60, s70, s6
	s_addc_u32 s61, s71, s7
	s_add_i32 s72, s37, 0x2000
	global_load_lds_dwordx4 v46, s[18:19]
	s_mov_b32 m0, s37
	s_add_u32 s6, s60, 0x10000
	v_lshl_or_b32 v44, v65, 9, v62
	global_load_lds_dwordx4 v40, s[60:61]
	s_mov_b32 m0, s72
	s_addc_u32 s7, s61, 0
	s_add_i32 s73, s37, 0x4000
	global_load_lds_dwordx4 v44, s[60:61]
	s_mov_b32 m0, s73
	s_add_i32 s74, s37, 0x6000
	global_load_lds_dwordx4 v40, s[6:7]
	s_mov_b32 m0, s74
	v_mov_b32_e32 v43, 0
	global_load_lds_dwordx4 v44, s[6:7]
	v_mov_b32_e32 v47, v43
	v_mov_b32_e32 v41, v43
	v_mov_b32_e32 v45, v43
	v_lshl_add_u64 v[6:7], s[62:63], 0, v[42:43]
	v_lshl_add_u64 v[4:5], s[62:63], 0, v[46:47]
	v_lshl_add_u64 v[2:3], s[60:61], 0, v[40:41]
	s_cmp_lg_u32 s4, 1
	v_lshl_add_u64 v[0:1], s[60:61], 0, v[44:45]
	s_setprio 1
	s_cbranch_scc1 .LBB0_299
	s_barrier
	s_setprio 0

; #define PG8_STAGE(bufoff, gbase, voff) do { _Pragma("unroll") for (int _i = 0; _i < 2; ++_i) \
;         __builtin_amdgcn_global_load_lds((const unsigned*)((const char*)(gbase) + (voff)[_i]), (LAS unsigned*)(lds + (bufoff) + ldsw + _i * 8192), 16, 0, 0); } while (0)
; #define PG8_BAR __builtin_amdgcn_s_barrier()
; template <class Epi, bool ALIGN_EPI = false, bool SP2 = true>
; __device__ __forceinline__ void gemm_phase(LAS unsigned char* lds, const Gemm g, const StaticOrder& S, const Epi& E) {
;     const int tid = threadIdx.x, wid = __builtin_amdgcn_readfirstlane(tid >> 6), lane = tid & 63, wr = wid >> 2, wc = wid & 3, fr = lane & 15, fq = lane >> 4;
;     const int K = g.K, nt = K / BK;
;     unsigned voffA[2], voffB[2];
; #pragma unroll
;     for (int i = 0; i < 2; ++i) { int R, C; stage_rc(tid * 16 + i * 8192, R, C); const int Rb = (R & ~31) + perm32(R & 31);
;         voffA[i] = (unsigned)(R * K + C) * 2u; voffB[i] = (unsigned)(Rb * K + C) * 2u; }
;     const size_t kstep = (size_t)(BK * 2);
;     const size_t hstep = (size_t)HALF * K * 2;
;     const size_t tstep = 2 * hstep;
;     const unsigned ldsw = (unsigned)wid * 1024u;
;     const int aoff = lds_byte(wr * 64 + fr, fq * 8), boff = lds_byte(wc * 32 + fr, fq * 8);
;     ...
;     Unit cur, nxt; int ui = 0;
;     if (!S.next(0, cur)) return;
;     f32x4 acc[2][2][4][2];
; #pragma unroll
;     for (int a = 0; a < 2; ++a)
; #pragma unroll
;         for (int b = 0; b < 2; ++b)
; #pragma unroll
;             for (int m = 0; m < 4; ++m)
; #pragma unroll
;                 for (int n = 0; n < 2; ++n) acc[a][b][m][n] = (f32x4){0.f, 0.f, 0.f, 0.f};
;     bf16x8 At[4][2], B0[2][2], B1[2][2];
;     const char* cA = (const char*)g.A + (size_t)cur.pm * tstep; const char* cB = (const char*)g.Bt + (size_t)(cur.pn + (cur.pm >= g.bsplit ? g.badd : 0)) * tstep;
;     if constexpr (SP2) {
;         PG8_STAGE(PG8_SB(0, 0), cB, voffB); PG8_STAGE(PG8_SB(0, 1), cB + hstep, voffB); PG8_STAGE(PG8_SA(0, 0), cA, voffA); PG8_STAGE(PG8_SA(0, 1), cA + hstep, voffA);
;         if (wr == 1) PG8_BAR;
.LBB0_315:
	s_ashr_i32 s0, s4, 3
	s_add_i32 s0, s6, s0
	s_ashr_i32 s1, s0, 31
	s_lshr_b32 s1, s1, 27
	s_add_i32 s1, s0, s1
	s_ashr_i32 s4, s1, 5
	s_andn2_b32 s1, s1, 31
	s_sub_i32 s0, s0, s1
	s_bfe_i32 s1, s0, 0x80000
	s_bfe_u32 s1, s1, 0x2000d
	s_add_i32 s1, s0, s1
	s_lshl_b32 s6, s4, 2
	s_bfe_i32 s4, s1, 0x80000
	s_and_b32 s1, s1, 0xfc
	s_sub_i32 s0, s0, s1
	s_sext_i32_i16 s4, s4
	s_sext_i32_i8 s0, s0
	s_lshr_b32 s5, s3, 8
	s_lshr_b32 s4, s4, 2
	s_add_i32 s18, s6, s0
	s_lshr_b32 s23, s3, 6
	s_ashr_i32 s19, s18, 31
	s_bfe_i64 s[6:7], s[4:5], 0x100000
	s_lshl_b32 s67, s23, 10
	s_lshl_b64 s[0:1], s[18:19], 20
	s_lshl_b64 s[6:7], s[6:7], 20
	s_add_u32 s60, s56, s6
	s_addc_u32 s61, s57, s7
	s_add_i32 s68, s67, 0
	v_lshl_or_b32 v130, v64, 12, v62
	s_add_i32 m0, s68, 0x10000
	v_lshl_or_b32 v134, v66, 12, v62
	global_load_lds_dwordx4 v130, s[60:61]
	s_add_i32 m0, s68, 0x12000
	s_add_u32 s6, s60, 0x80000
	global_load_lds_dwordx4 v134, s[60:61]
	s_addc_u32 s7, s61, 0
	s_add_i32 m0, s68, 0x14000
	v_lshl_or_b32 v128, v63, 12, v62
	global_load_lds_dwordx4 v130, s[6:7]
	s_add_i32 m0, s68, 0x16000
	s_add_u32 s0, s38, s0
	s_addc_u32 s1, s39, s1
	s_add_i32 s69, s68, 0x2000
	global_load_lds_dwordx4 v134, s[6:7]
	s_mov_b32 m0, s68
	s_add_u32 s6, s0, 0x80000
	v_lshl_or_b32 v132, v65, 12, v62
	global_load_lds_dwordx4 v128, s[0:1]
	s_mov_b32 m0, s69
	s_addc_u32 s7, s1, 0
	s_add_i32 s70, s68, 0x4000
	global_load_lds_dwordx4 v132, s[0:1]
	s_mov_b32 m0, s70
	s_add_i32 s71, s68, 0x6000
	global_load_lds_dwordx4 v128, s[6:7]
	s_mov_b32 m0, s71
	v_mov_b32_e32 v131, 0
	global_load_lds_dwordx4 v132, s[6:7]
	v_mov_b32_e32 v135, v131
	v_mov_b32_e32 v129, v131
	v_mov_b32_e32 v133, v131
	v_lshl_add_u64 v[6:7], s[60:61], 0, v[130:131]
	v_lshl_add_u64 v[4:5], s[60:61], 0, v[134:135]
	v_lshl_add_u64 v[2:3], s[0:1], 0, v[128:129]
	s_cmp_lg_u32 s5, 1
	v_lshl_add_u64 v[0:1], s[0:1], 0, v[132:133]
	s_setprio 1
	s_cbranch_scc1 .LBB0_317
	s_barrier
	s_setprio 0

; #define PG8_STAGE(bufoff, gbase, voff) do { _Pragma("unroll") for (int _i = 0; _i < 2; ++_i) \
;         __builtin_amdgcn_global_load_lds((const unsigned*)((const char*)(gbase) + (voff)[_i]), (LAS unsigned*)(lds + (bufoff) + ldsw + _i * 8192), 16, 0, 0); } while (0)
; #define PG8_BAR __builtin_amdgcn_s_barrier()
; template <class Epi, bool ALIGN_EPI = false, bool SP2 = true>
; __device__ __forceinline__ void gemm_phase(LAS unsigned char* lds, const Gemm g, const StaticOrder& S, const Epi& E) {
;     const int tid = threadIdx.x, wid = __builtin_amdgcn_readfirstlane(tid >> 6), lane = tid & 63, wr = wid >> 2, wc = wid & 3, fr = lane & 15, fq = lane >> 4;
;     const int K = g.K, nt = K / BK;
;     unsigned voffA[2], voffB[2];
; #pragma unroll
;     for (int i = 0; i < 2; ++i) { int R, C; stage_rc(tid * 16 + i * 8192, R, C); const int Rb = (R & ~31) + perm32(R & 31);
;         voffA[i] = (unsigned)(R * K + C) * 2u; voffB[i] = (unsigned)(Rb * K + C) * 2u; }
;     const size_t kstep = (size_t)(BK * 2);
;     const size_t hstep = (size_t)HALF * K * 2;
;     const size_t tstep = 2 * hstep;
;     const unsigned ldsw = (unsigned)wid * 1024u;
;     const int aoff = lds_byte(wr * 64 + fr, fq * 8), boff = lds_byte(wc * 32 + fr, fq * 8);
;     ...
;     Unit cur, nxt; int ui = 0;
;     if (!S.next(0, cur)) return;
;     f32x4 acc[2][2][4][2];
; #pragma unroll
;     for (int a = 0; a < 2; ++a)
; #pragma unroll
;         for (int b = 0; b < 2; ++b)
; #pragma unroll
;             for (int m = 0; m < 4; ++m)
; #pragma unroll
;                 for (int n = 0; n < 2; ++n) acc[a][b][m][n] = (f32x4){0.f, 0.f, 0.f, 0.f};
;     bf16x8 At[4][2], B0[2][2], B1[2][2];
;     const char* cA = (const char*)g.A + (size_t)cur.pm * tstep; const char* cB = (const char*)g.Bt + (size_t)(cur.pn + (cur.pm >= g.bsplit ? g.badd : 0)) * tstep;
;     if constexpr (SP2) {
;         PG8_STAGE(PG8_SB(0, 0), cB, voffB); PG8_STAGE(PG8_SB(0, 1), cB + hstep, voffB); PG8_STAGE(PG8_SA(0, 0), cA, voffA); PG8_STAGE(PG8_SA(0, 1), cA + hstep, voffA);
;         if (wr == 1) PG8_BAR;
.LBB0_429:
	v_lshrrev_b32_e32 v2, 1, v164
	v_and_b32_e32 v11, 24, v2
	v_lshrrev_b32_e32 v2, 5, v164
	s_ashr_i32 s4, s7, 3
	v_and_b32_e32 v2, 4, v2
	v_bfe_u32 v3, v164, 2, 2
	v_lshlrev_b32_e32 v0, 4, v164
	v_and_b32_e32 v1, 32, v164
	v_bfe_u32 v10, v164, 2, 4
	v_or3_b32 v2, v2, v3, v11
	v_lshrrev_b32_e32 v3, 3, v164
	s_movk_i32 s7, 0x70
	s_add_i32 s4, s6, s4
	v_bitop3_b32 v8, v0, v1, 48 bitop3:0x6c
	v_and_b32_e32 v9, 64, v164
	v_and_or_b32 v4, v3, s7, v10
	s_movk_i32 s7, 0x60
	v_add_u32_e32 v12, 0x2000, v0
	s_ashr_i32 s6, s4, 31
	v_or_b32_e32 v1, v8, v9
	v_and_or_b32 v3, v3, s7, v2
	v_lshrrev_b32_e32 v0, 7, v12
	s_movk_i32 s7, 0xf0
	s_lshr_b32 s6, s6, 27
	v_lshl_or_b32 v168, v3, 12, v1
	v_and_or_b32 v3, v0, s7, v10
	s_movk_i32 s7, 0xe0
	s_add_i32 s6, s4, s6
	v_and_or_b32 v0, v0, s7, v2
	s_ashr_i32 s7, s6, 5
	s_andn2_b32 s6, s6, 31
	s_sub_i32 s6, s4, s6
	s_bfe_i32 s4, s6, 0x80000
	s_bfe_u32 s4, s4, 0x2000d
	s_add_i32 s17, s6, s4
	s_bfe_i32 s4, s17, 0x80000
	s_and_b32 s17, s17, 0xfc
	s_sub_i32 s6, s6, s17
	s_lshl_b32 s7, s7, 2
	s_sext_i32_i16 s4, s4
	s_sext_i32_i8 s6, s6
	s_lshr_b32 s5, s18, 8
	s_lshr_b32 s4, s4, 2
	s_add_i32 s30, s7, s6
	s_lshr_b32 s16, s18, 6
	s_ashr_i32 s31, s30, 31
	s_bfe_i64 s[22:23], s[4:5], 0x100000
	s_lshl_b32 s60, s16, 10
	s_lshl_b64 s[6:7], s[30:31], 20
	s_lshl_b64 s[22:23], s[22:23], 20
	s_add_u32 s56, s52, s22
	s_addc_u32 s57, s53, s23
	s_add_i32 s31, s60, 0
	s_add_i32 m0, s31, 0x10000
	v_lshl_or_b32 v172, v0, 12, v1
	global_load_lds_dwordx4 v168, s[56:57]
	s_add_i32 m0, s31, 0x12000
	s_add_u32 s22, s56, 0x80000
	global_load_lds_dwordx4 v172, s[56:57]
	s_addc_u32 s23, s57, 0
	s_add_i32 m0, s31, 0x14000
	v_lshl_or_b32 v166, v4, 12, v1
	global_load_lds_dwordx4 v168, s[22:23]
	s_add_i32 m0, s31, 0x16000
	s_add_u32 s36, s10, s6
	s_addc_u32 s37, s11, s7
	s_add_i32 s61, s31, 0x2000
	global_load_lds_dwordx4 v172, s[22:23]
	s_mov_b32 m0, s31
	s_add_u32 s6, s36, 0x80000
	v_lshl_or_b32 v170, v3, 12, v1
	global_load_lds_dwordx4 v166, s[36:37]
	s_mov_b32 m0, s61
	s_addc_u32 s7, s37, 0
	s_add_i32 s62, s31, 0x4000
	global_load_lds_dwordx4 v170, s[36:37]
	s_mov_b32 m0, s62
	s_add_i32 s63, s31, 0x6000
	global_load_lds_dwordx4 v166, s[6:7]
	s_mov_b32 m0, s63
	v_mov_b32_e32 v169, 0
	global_load_lds_dwordx4 v170, s[6:7]
	v_mov_b32_e32 v173, v169
	v_mov_b32_e32 v167, v169
	v_mov_b32_e32 v171, v169
	s_cmp_eq_u32 s5, 1
	s_mov_b32 s64, 0
	s_mov_b32 s65, 0x10000
	v_lshl_add_u64 v[6:7], s[56:57], 0, v[168:169]
	v_lshl_add_u64 v[4:5], s[56:57], 0, v[172:173]
	v_lshl_add_u64 v[0:1], s[36:37], 0, v[166:167]
	s_cselect_b64 s[6:7], -1, 0
	s_cmp_lg_u32 s5, 1
	v_lshl_add_u64 v[2:3], s[36:37], 0, v[170:171]
	s_setprio 1
	s_cbranch_scc1 .LBB0_431
	s_barrier
	s_setprio 0

; #define PG8_STAGE(bufoff, gbase, voff) do { _Pragma("unroll") for (int _i = 0; _i < 2; ++_i) \
;         __builtin_amdgcn_global_load_lds((const unsigned*)((const char*)(gbase) + (voff)[_i]), (LAS unsigned*)(lds + (bufoff) + ldsw + _i * 8192), 16, 0, 0); } while (0)
; #define PG8_BAR __builtin_amdgcn_s_barrier()
; template <class Epi, bool ALIGN_EPI = false, bool SP2 = true>
; __device__ __forceinline__ void gemm_phase(LAS unsigned char* lds, const Gemm g, const StaticOrder& S, const Epi& E) {
;     const int tid = threadIdx.x, wid = __builtin_amdgcn_readfirstlane(tid >> 6), lane = tid & 63, wr = wid >> 2, wc = wid & 3, fr = lane & 15, fq = lane >> 4;
;     const int K = g.K, nt = K / BK;
;     unsigned voffA[2], voffB[2];
; #pragma unroll
;     for (int i = 0; i < 2; ++i) { int R, C; stage_rc(tid * 16 + i * 8192, R, C); const int Rb = (R & ~31) + perm32(R & 31);
;         voffA[i] = (unsigned)(R * K + C) * 2u; voffB[i] = (unsigned)(Rb * K + C) * 2u; }
;     const size_t kstep = (size_t)(BK * 2);
;     const size_t hstep = (size_t)HALF * K * 2;
;     const size_t tstep = 2 * hstep;
;     const unsigned ldsw = (unsigned)wid * 1024u;
;     const int aoff = lds_byte(wr * 64 + fr, fq * 8), boff = lds_byte(wc * 32 + fr, fq * 8);
;     ...
;     Unit cur, nxt; int ui = 0;
;     if (!S.next(0, cur)) return;
;     f32x4 acc[2][2][4][2];
; #pragma unroll
;     for (int a = 0; a < 2; ++a)
; #pragma unroll
;         for (int b = 0; b < 2; ++b)
; #pragma unroll
;             for (int m = 0; m < 4; ++m)
; #pragma unroll
;                 for (int n = 0; n < 2; ++n) acc[a][b][m][n] = (f32x4){0.f, 0.f, 0.f, 0.f};
;     bf16x8 At[4][2], B0[2][2], B1[2][2];
;     const char* cA = (const char*)g.A + (size_t)cur.pm * tstep; const char* cB = (const char*)g.Bt + (size_t)(cur.pn + (cur.pm >= g.bsplit ? g.badd : 0)) * tstep;
;     if constexpr (SP2) {
;         PG8_STAGE(PG8_SB(0, 0), cB, voffB); PG8_STAGE(PG8_SB(0, 1), cB + hstep, voffB); PG8_STAGE(PG8_SA(0, 0), cA, voffA); PG8_STAGE(PG8_SA(0, 1), cA + hstep, voffA);
;         if (wr == 1) PG8_BAR;
.LBB0_505:
	s_andn2_b64 vcc, exec, s[4:5]
	s_cbranch_vccnz .LBB0_571
	s_waitcnt vmcnt(0)
	v_lshrrev_b32_e32 v2, 1, v164
	v_and_b32_e32 v11, 24, v2
	v_lshrrev_b32_e32 v2, 5, v164
	v_and_b32_e32 v2, 4, v2
	v_bfe_u32 v3, v164, 2, 2
	v_lshlrev_b32_e32 v0, 4, v164
	v_and_b32_e32 v1, 32, v164
	v_bfe_u32 v10, v164, 2, 4
	v_or3_b32 v2, v2, v3, v11
	v_lshrrev_b32_e32 v3, 3, v164
	s_movk_i32 s4, 0x70
	v_bitop3_b32 v8, v0, v1, 48 bitop3:0x6c
	v_and_b32_e32 v9, 64, v164
	v_and_or_b32 v4, v3, s4, v10
	s_movk_i32 s4, 0x60
	v_add_u32_e32 v12, 0x2000, v0
	v_or_b32_e32 v1, v8, v9
	v_and_or_b32 v3, v3, s4, v2
	v_lshrrev_b32_e32 v0, 7, v12
	s_movk_i32 s4, 0xf0
	v_lshl_or_b32 v130, v3, 12, v1
	v_and_or_b32 v3, v0, s4, v10
	s_movk_i32 s4, 0xe0
	v_and_or_b32 v0, v0, s4, v2
	s_lshr_b32 s4, s26, 6
	s_ashr_i32 s19, s18, 31
	s_ashr_i32 s9, s8, 31
	s_lshr_b32 s29, s26, 8
	s_lshl_b32 s64, s4, 10
	s_lshl_b64 s[6:7], s[18:19], 20
	s_lshl_b64 s[10:11], s[8:9], 20
	s_add_u32 s60, s40, s10
	s_addc_u32 s61, s41, s11
	s_add_i32 s65, s64, 0
	s_add_i32 m0, s65, 0x10000
	v_lshl_or_b32 v134, v0, 12, v1
	global_load_lds_dwordx4 v130, s[60:61]
	s_add_i32 m0, s65, 0x12000
	s_add_u32 s10, s60, 0x80000
	global_load_lds_dwordx4 v134, s[60:61]
	s_addc_u32 s11, s61, 0
	s_add_i32 m0, s65, 0x14000
	v_lshl_or_b32 v128, v4, 12, v1
	global_load_lds_dwordx4 v130, s[10:11]
	s_add_i32 m0, s65, 0x16000
	v_lshl_or_b32 v132, v3, 12, v1
	global_load_lds_dwordx4 v134, s[10:11]
	s_add_u32 s10, s20, s6
	s_addc_u32 s11, s21, s7
	s_add_i32 s66, s65, 0x2000
	s_mov_b32 m0, s65
	s_add_u32 s6, s10, 0x80000
	global_load_lds_dwordx4 v128, s[10:11]
	s_mov_b32 m0, s66
	s_addc_u32 s7, s11, 0
	s_add_i32 s67, s65, 0x4000
	global_load_lds_dwordx4 v132, s[10:11]
	s_mov_b32 m0, s67
	s_add_i32 s68, s65, 0x6000
	global_load_lds_dwordx4 v128, s[6:7]
	s_mov_b32 m0, s68
	v_mov_b32_e32 v137, 0
	global_load_lds_dwordx4 v132, s[6:7]
	v_mov_b32_e32 v131, v137
	v_mov_b32_e32 v135, v137
	v_mov_b32_e32 v129, v137
	v_mov_b32_e32 v133, v137
	s_cmp_eq_u32 s29, 1
	s_mov_b32 s19, 0
	v_lshl_add_u64 v[6:7], s[60:61], 0, v[130:131]
	v_lshl_add_u64 v[4:5], s[60:61], 0, v[134:135]
	v_lshl_add_u64 v[0:1], s[10:11], 0, v[128:129]
	s_cselect_b64 s[22:23], -1, 0
	s_cmp_lg_u32 s29, 1
	v_lshl_add_u64 v[2:3], s[10:11], 0, v[132:133]
	s_setprio 1
	s_cbranch_scc1 .LBB0_508
	s_barrier
	s_setprio 0

; #define PG8_STAGE(bufoff, gbase, voff) do { _Pragma("unroll") for (int _i = 0; _i < 2; ++_i) \
;         __builtin_amdgcn_global_load_lds((const unsigned*)((const char*)(gbase) + (voff)[_i]), (LAS unsigned*)(lds + (bufoff) + ldsw + _i * 8192), 16, 0, 0); } while (0)
; #define PG8_BAR __builtin_amdgcn_s_barrier()
; template <class Epi, bool ALIGN_EPI = false, bool SP2 = true>
; __device__ __forceinline__ void gemm_phase(LAS unsigned char* lds, const Gemm g, const StaticOrder& S, const Epi& E) {
;     const int tid = threadIdx.x, wid = __builtin_amdgcn_readfirstlane(tid >> 6), lane = tid & 63, wr = wid >> 2, wc = wid & 3, fr = lane & 15, fq = lane >> 4;
;     const int K = g.K, nt = K / BK;
;     unsigned voffA[2], voffB[2];
; #pragma unroll
;     for (int i = 0; i < 2; ++i) { int R, C; stage_rc(tid * 16 + i * 8192, R, C); const int Rb = (R & ~31) + perm32(R & 31);
;         voffA[i] = (unsigned)(R * K + C) * 2u; voffB[i] = (unsigned)(Rb * K + C) * 2u; }
;     const size_t kstep = (size_t)(BK * 2);
;     const size_t hstep = (size_t)HALF * K * 2;
;     const size_t tstep = 2 * hstep;
;     const unsigned ldsw = (unsigned)wid * 1024u;
;     const int aoff = lds_byte(wr * 64 + fr, fq * 8), boff = lds_byte(wc * 32 + fr, fq * 8);
;     ...
;     Unit cur, nxt; int ui = 0;
;     if (!S.next(0, cur)) return;
;     f32x4 acc[2][2][4][2];
; #pragma unroll
;     for (int a = 0; a < 2; ++a)
; #pragma unroll
;         for (int b = 0; b < 2; ++b)
; #pragma unroll
;             for (int m = 0; m < 4; ++m)
; #pragma unroll
;                 for (int n = 0; n < 2; ++n) acc[a][b][m][n] = (f32x4){0.f, 0.f, 0.f, 0.f};
;     bf16x8 At[4][2], B0[2][2], B1[2][2];
;     const char* cA = (const char*)g.A + (size_t)cur.pm * tstep; const char* cB = (const char*)g.Bt + (size_t)(cur.pn + (cur.pm >= g.bsplit ? g.badd : 0)) * tstep;
;     if constexpr (SP2) {
;         PG8_STAGE(PG8_SB(0, 0), cB, voffB); PG8_STAGE(PG8_SB(0, 1), cB + hstep, voffB); PG8_STAGE(PG8_SA(0, 0), cA, voffA); PG8_STAGE(PG8_SA(0, 1), cA + hstep, voffA);
;         if (wr == 1) PG8_BAR;
.LBB0_736:
	v_lshrrev_b32_e32 v148, 1, v164
	s_waitcnt vmcnt(0)
	v_lshrrev_b32_e32 v3, 5, v164
	v_and_b32_e32 v2, 24, v148
	v_and_b32_e32 v3, 4, v3
	v_bfe_u32 v4, v164, 2, 2
	v_lshlrev_b32_e32 v0, 4, v164
	v_and_b32_e32 v1, 32, v164
	v_bfe_u32 v10, v164, 2, 4
	v_or3_b32 v2, v3, v4, v2
	v_lshrrev_b32_e32 v3, 3, v164
	s_movk_i32 s1, 0x70
	v_bitop3_b32 v8, v0, v1, 48 bitop3:0x6c
	v_and_b32_e32 v9, 64, v164
	v_and_or_b32 v4, v3, s1, v10
	s_movk_i32 s1, 0x60
	v_add_u32_e32 v11, 0x2000, v0
	s_ashr_i32 s0, s5, 3
	v_or_b32_e32 v1, v8, v9
	v_and_or_b32 v3, v3, s1, v2
	v_lshrrev_b32_e32 v0, 7, v11
	s_movk_i32 s1, 0xf0
	v_lshl_or_b32 v130, v3, 12, v1
	v_and_or_b32 v3, v0, s1, v10
	s_movk_i32 s1, 0xe0
	s_add_i32 s0, s4, s0
	v_and_or_b32 v0, v0, s1, v2
	s_ashr_i32 s1, s0, 31
	s_lshr_b32 s1, s1, 27
	s_add_i32 s1, s0, s1
	s_ashr_i32 s4, s1, 5
	s_andn2_b32 s1, s1, 31
	s_sub_i32 s0, s0, s1
	s_bfe_i32 s1, s0, 0x80000
	s_bfe_u32 s1, s1, 0x2000d
	s_add_i32 s1, s0, s1
	s_lshl_b32 s6, s4, 2
	s_bfe_i32 s4, s1, 0x80000
	s_and_b32 s1, s1, 0xfc
	s_sub_i32 s0, s0, s1
	s_sext_i32_i16 s4, s4
	s_sext_i32_i8 s0, s0
	s_lshr_b32 s5, s3, 8
	s_lshr_b32 s4, s4, 2
	s_add_i32 s10, s6, s0
	s_lshr_b32 s15, s3, 6
	s_ashr_i32 s11, s10, 31
	s_bfe_i64 s[6:7], s[4:5], 0x100000
	s_lshl_b32 s57, s15, 10
	s_lshl_b64 s[0:1], s[10:11], 20
	s_lshl_b64 s[6:7], s[6:7], 20
	s_add_u32 s36, s24, s6
	s_addc_u32 s37, s25, s7
	s_add_i32 s58, s57, 0
	s_add_i32 m0, s58, 0x10000
	v_lshl_or_b32 v134, v0, 12, v1
	global_load_lds_dwordx4 v130, s[36:37]
	s_add_i32 m0, s58, 0x12000
	s_add_u32 s6, s36, 0x80000
	global_load_lds_dwordx4 v134, s[36:37]
	s_addc_u32 s7, s37, 0
	s_add_i32 m0, s58, 0x14000
	v_lshl_or_b32 v128, v4, 12, v1
	global_load_lds_dwordx4 v130, s[6:7]
	s_add_i32 m0, s58, 0x16000
	s_add_u32 s0, s38, s0
	s_addc_u32 s1, s39, s1
	s_add_i32 s59, s58, 0x2000
	global_load_lds_dwordx4 v134, s[6:7]
	s_mov_b32 m0, s58
	s_add_u32 s6, s0, 0x80000
	v_lshl_or_b32 v132, v3, 12, v1
	global_load_lds_dwordx4 v128, s[0:1]
	s_mov_b32 m0, s59
	s_addc_u32 s7, s1, 0
	s_add_i32 s60, s58, 0x4000
	global_load_lds_dwordx4 v132, s[0:1]
	s_mov_b32 m0, s60
	s_add_i32 s61, s58, 0x6000
	global_load_lds_dwordx4 v128, s[6:7]
	s_mov_b32 m0, s61
	v_mov_b32_e32 v131, 0
	global_load_lds_dwordx4 v132, s[6:7]
	v_mov_b32_e32 v135, v131
	v_mov_b32_e32 v129, v131
	v_mov_b32_e32 v133, v131
	v_lshl_add_u64 v[6:7], s[36:37], 0, v[130:131]
	v_lshl_add_u64 v[4:5], s[36:37], 0, v[134:135]
	v_lshl_add_u64 v[2:3], s[0:1], 0, v[128:129]
	s_cmp_lg_u32 s5, 1
	v_lshl_add_u64 v[0:1], s[0:1], 0, v[132:133]
	s_setprio 1
	s_cbranch_scc1 .LBB0_738
	s_barrier
	s_setprio 0

; #define PG8_STAGE(bufoff, gbase, voff) do { _Pragma("unroll") for (int _i = 0; _i < 2; ++_i) \
;         __builtin_amdgcn_global_load_lds((const unsigned*)((const char*)(gbase) + (voff)[_i]), (LAS unsigned*)(lds + (bufoff) + ldsw + _i * 8192), 16, 0, 0); } while (0)
; #define PG8_BAR __builtin_amdgcn_s_barrier()
; template <class Epi, bool ALIGN_EPI = false, bool SP2 = true>
; __device__ __forceinline__ void gemm_phase(LAS unsigned char* lds, const Gemm g, const StaticOrder& S, const Epi& E) {
;     const int tid = threadIdx.x, wid = __builtin_amdgcn_readfirstlane(tid >> 6), lane = tid & 63, wr = wid >> 2, wc = wid & 3, fr = lane & 15, fq = lane >> 4;
;     const int K = g.K, nt = K / BK;
;     unsigned voffA[2], voffB[2];
; #pragma unroll
;     for (int i = 0; i < 2; ++i) { int R, C; stage_rc(tid * 16 + i * 8192, R, C); const int Rb = (R & ~31) + perm32(R & 31);
;         voffA[i] = (unsigned)(R * K + C) * 2u; voffB[i] = (unsigned)(Rb * K + C) * 2u; }
;     const size_t kstep = (size_t)(BK * 2);
;     const size_t hstep = (size_t)HALF * K * 2;
;     const size_t tstep = 2 * hstep;
;     const unsigned ldsw = (unsigned)wid * 1024u;
;     const int aoff = lds_byte(wr * 64 + fr, fq * 8), boff = lds_byte(wc * 32 + fr, fq * 8);
;     ...
;     Unit cur, nxt; int ui = 0;
;     if (!S.next(0, cur)) return;
;     f32x4 acc[2][2][4][2];
; #pragma unroll
;     for (int a = 0; a < 2; ++a)
; #pragma unroll
;         for (int b = 0; b < 2; ++b)
; #pragma unroll
;             for (int m = 0; m < 4; ++m)
; #pragma unroll
;                 for (int n = 0; n < 2; ++n) acc[a][b][m][n] = (f32x4){0.f, 0.f, 0.f, 0.f};
;     bf16x8 At[4][2], B0[2][2], B1[2][2];
;     const char* cA = (const char*)g.A + (size_t)cur.pm * tstep; const char* cB = (const char*)g.Bt + (size_t)(cur.pn + (cur.pm >= g.bsplit ? g.badd : 0)) * tstep;
;     if constexpr (SP2) {
;         PG8_STAGE(PG8_SB(0, 0), cB, voffB); PG8_STAGE(PG8_SB(0, 1), cB + hstep, voffB); PG8_STAGE(PG8_SA(0, 0), cA, voffA); PG8_STAGE(PG8_SA(0, 1), cA + hstep, voffA);
;         if (wr == 1) PG8_BAR;
.LBB0_843:
	s_waitcnt vmcnt(0)
	v_lshrrev_b32_e32 v2, 1, v164
	v_and_b32_e32 v11, 24, v2
	v_lshrrev_b32_e32 v2, 5, v164
	v_and_b32_e32 v2, 4, v2
	v_bfe_u32 v3, v164, 2, 2
	v_lshlrev_b32_e32 v0, 4, v164
	v_and_b32_e32 v1, 32, v164
	v_bfe_u32 v10, v164, 2, 4
	v_or3_b32 v2, v2, v3, v11
	v_lshrrev_b32_e32 v3, 3, v164
	s_movk_i32 s5, 0x70
	s_add_i32 s0, s4, s0
	v_bitop3_b32 v8, v0, v1, 48 bitop3:0x6c
	v_and_b32_e32 v9, 64, v164
	v_and_or_b32 v4, v3, s5, v10
	s_movk_i32 s5, 0x60
	v_add_u32_e32 v12, 0x2000, v0
	s_ashr_i32 s4, s0, 31
	v_or_b32_e32 v1, v8, v9
	v_and_or_b32 v3, v3, s5, v2
	v_lshrrev_b32_e32 v0, 7, v12
	s_movk_i32 s5, 0xf0
	s_lshr_b32 s4, s4, 27
	v_lshl_or_b32 v168, v3, 12, v1
	v_and_or_b32 v3, v0, s5, v10
	s_movk_i32 s5, 0xe0
	s_add_i32 s4, s0, s4
	v_and_or_b32 v0, v0, s5, v2
	s_ashr_i32 s5, s4, 5
	s_and_b32 s4, s4, 0xffe0
	s_sub_i32 s4, s0, s4
	s_bfe_i32 s0, s4, 0x80000
	s_bfe_u32 s0, s0, 0x2000d
	s_add_i32 s7, s4, s0
	s_bfe_i32 s0, s7, 0x80000
	s_and_b32 s7, s7, 0xfc
	s_sub_i32 s4, s4, s7
	s_lshl_b32 s5, s5, 2
	s_sext_i32_i16 s0, s0
	s_sext_i32_i8 s4, s4
	s_lshr_b32 s1, s10, 8
	s_lshr_b32 s0, s0, 2
	s_add_i32 s42, s5, s4
	s_lshr_b32 s6, s10, 6
	s_ashr_i32 s43, s42, 31
	s_bfe_i64 s[8:9], s[0:1], 0x100000
	s_lshl_b32 s33, s6, 10
	s_lshl_b64 s[4:5], s[42:43], 20
	s_lshl_b64 s[8:9], s[8:9], 20
	s_add_u32 s44, s22, s8
	s_addc_u32 s45, s23, s9
	s_add_i32 s35, s33, 0
	s_add_i32 m0, s35, 0x10000
	v_lshl_or_b32 v172, v0, 12, v1
	global_load_lds_dwordx4 v168, s[44:45]
	s_add_i32 m0, s35, 0x12000
	s_add_u32 s8, s44, 0x80000
	global_load_lds_dwordx4 v172, s[44:45]
	s_addc_u32 s9, s45, 0
	s_add_i32 m0, s35, 0x14000
	v_lshl_or_b32 v166, v4, 12, v1
	global_load_lds_dwordx4 v168, s[8:9]
	s_add_i32 m0, s35, 0x16000
	s_add_u32 s46, s52, s4
	s_addc_u32 s47, s53, s5
	s_add_i32 s43, s35, 0x2000
	global_load_lds_dwordx4 v172, s[8:9]
	s_mov_b32 m0, s35
	s_add_u32 s4, s46, 0x80000
	v_lshl_or_b32 v170, v3, 12, v1
	global_load_lds_dwordx4 v166, s[46:47]
	s_mov_b32 m0, s43
	s_addc_u32 s5, s47, 0
	s_add_i32 s48, s35, 0x4000
	global_load_lds_dwordx4 v170, s[46:47]
	s_mov_b32 m0, s48
	s_add_i32 s49, s35, 0x6000
	global_load_lds_dwordx4 v166, s[4:5]
	s_mov_b32 m0, s49
	v_mov_b32_e32 v169, 0
	global_load_lds_dwordx4 v170, s[4:5]
	v_mov_b32_e32 v173, v169
	v_mov_b32_e32 v167, v169
	v_mov_b32_e32 v171, v169
	s_cmp_eq_u32 s1, 1
	s_mov_b32 s50, 0
	s_mov_b32 s51, 0x10000
	v_lshl_add_u64 v[6:7], s[44:45], 0, v[168:169]
	v_lshl_add_u64 v[4:5], s[44:45], 0, v[172:173]
	v_lshl_add_u64 v[0:1], s[46:47], 0, v[166:167]
	s_cselect_b64 s[4:5], -1, 0
	s_cmp_lg_u32 s1, 1
	v_lshl_add_u64 v[2:3], s[46:47], 0, v[170:171]
	s_setprio 1
	s_cbranch_scc1 .LBB0_845
	s_barrier
	s_setprio 0
